# 2-deep pipelined x->bf16 prologue loop on top of reversed N=1024 unit order and trimmed K-loop DMA m0 handling
# baseline (speedup 1.0000x reference)
; __device__ __forceinline__ unsigned cvt_pk_bf16(float lo, float hi) { unsigned r; asm volatile("v_cvt_pk_bf16_f32 %0, %1, %2" : "=v"(r) : "v"(lo), "v"(hi)); return r; }
; __global__ void __launch_bounds__(512, 2) __attribute__((amdgpu_waves_per_eu(2, 2))) mk_fwd(Args a_) {
;     ...
;             const float* x_in = a.in[0]; bf16_t* XB = (bf16_t*)(ws + WS_XB);
;             for (size_t i = (size_t)gw * 64 + lane; i < (size_t)MTOK * DM / 8; i += (size_t)NGW * 64) {
;                 const f32x4 v0 = ((const f32x4*)x_in)[2 * i], v1 = ((const f32x4*)x_in)[2 * i + 1];
;                 u32x4 w; w.x = cvt_pk_bf16(v0.x, v0.y); w.y = cvt_pk_bf16(v0.z, v0.w); w.z = cvt_pk_bf16(v1.x, v1.y); w.w = cvt_pk_bf16(v1.z, v1.w);
;                 ((u32x4*)XB)[i] = w;
.LBB0_54:
	s_or_b64 exec, exec, s[4:5]
	s_ashr_i32 s21, s20, 31
	s_lshl_b64 s[6:7], s[20:21], 6
	v_mov_b64_e32 v[2:3], 0x3fffff
	v_cmp_gt_u64_e32 vcc, s[6:7], v[2:3]
	s_mov_b64 s[4:5], 0x3fffff
	s_cbranch_vccnz .LBB0_571
	s_ashr_i32 s19, s18, 31
	s_load_dwordx2 s[10:11], s[16:17], 0x0
	v_or_b32_e32 v2, s6, v11
	v_mov_b32_e32 v3, s7
	s_lshl_b64 s[6:7], s[18:19], 6
	s_lshl_b64 s[8:9], s[20:21], 10
	s_waitcnt lgkmcnt(0)
	s_add_u32 s8, s2, s8
	v_lshlrev_b32_e32 v6, 4, v11
	v_mov_b32_e32 v7, 0
	s_addc_u32 s9, s3, s9
	v_lshl_add_u64 v[4:5], s[8:9], 0, v[6:7]
	s_mov_b64 s[8:9], 0x6400000
	v_lshl_add_u64 v[4:5], v[4:5], 0, s[8:9]
	s_lshl_b64 s[8:9], s[18:19], 10
	s_lshl_b64 s[12:13], s[20:21], 11
	s_add_u32 s10, s10, s12
	v_lshlrev_b32_e32 v6, 5, v11
	s_addc_u32 s11, s11, s13
	v_lshl_add_u64 v[6:7], s[10:11], 0, v[6:7]
	v_lshl_add_u64 v[6:7], v[6:7], 0, 16
	s_lshl_b64 s[12:13], s[18:19], 11
	s_mov_b64 s[10:11], exec

; __device__ __forceinline__ unsigned cvt_pk_bf16(float lo, float hi) { unsigned r; asm volatile("v_cvt_pk_bf16_f32 %0, %1, %2" : "=v"(r) : "v"(lo), "v"(hi)); return r; }
; __global__ void __launch_bounds__(512, 2) __attribute__((amdgpu_waves_per_eu(2, 2))) mk_fwd(Args a_) {
;     ...
;             for (size_t i = (size_t)gw * 64 + lane; i < (size_t)MTOK * DM / 8; i += (size_t)NGW * 64) {
;                 const f32x4 v0 = ((const f32x4*)x_in)[2 * i], v1 = ((const f32x4*)x_in)[2 * i + 1];
;                 u32x4 w; w.x = cvt_pk_bf16(v0.x, v0.y); w.y = cvt_pk_bf16(v0.z, v0.w); w.z = cvt_pk_bf16(v1.x, v1.y); w.w = cvt_pk_bf16(v1.z, v1.w);
;                 ((u32x4*)XB)[i] = w;
;             }
.Lxc_loop:
	v_lshl_add_u64 v[2:3], v[2:3], 0, s[6:7]
	v_cmp_lt_u64_e32 vcc, s[4:5], v[2:3]
	v_lshl_add_u64 v[6:7], v[6:7], 0, s[12:13]
	s_mov_b64 s[22:23], exec
	s_andn2_b64 s[24:25], exec, vcc
	s_cbranch_scc0 .Lxc_lastA
	s_mov_b64 exec, s[24:25]
	global_load_dwordx4 v[16:19], v[6:7], off offset:-16
	global_load_dwordx4 v[20:23], v[6:7], off
	s_mov_b64 exec, s[22:23]
	s_waitcnt vmcnt(2)
	v_cvt_pk_bf16_f32 v8, v8, v9
	v_cvt_pk_bf16_f32 v9, v10, v11
	v_cvt_pk_bf16_f32 v10, v12, v13
	v_cvt_pk_bf16_f32 v11, v14, v15
	global_store_dwordx4 v[4:5], v[8:11], off
	v_lshl_add_u64 v[4:5], v[4:5], 0, s[8:9]
	s_mov_b64 exec, s[24:25]
	v_lshl_add_u64 v[2:3], v[2:3], 0, s[6:7]
	v_cmp_lt_u64_e32 vcc, s[4:5], v[2:3]
	v_lshl_add_u64 v[6:7], v[6:7], 0, s[12:13]
	s_andn2_b64 s[26:27], exec, vcc
	s_cbranch_scc0 .Lxc_lastB
	s_mov_b64 exec, s[26:27]
	global_load_dwordx4 v[8:11], v[6:7], off offset:-16
	global_load_dwordx4 v[12:15], v[6:7], off
	s_mov_b64 exec, s[24:25]
	s_waitcnt vmcnt(3)
	v_cvt_pk_bf16_f32 v16, v16, v17
	v_cvt_pk_bf16_f32 v17, v18, v19
	v_cvt_pk_bf16_f32 v18, v20, v21
	v_cvt_pk_bf16_f32 v19, v22, v23
	global_store_dwordx4 v[4:5], v[16:19], off
	v_lshl_add_u64 v[4:5], v[4:5], 0, s[8:9]
	s_mov_b64 exec, s[26:27]
	s_branch .Lxc_loop
.Lxc_lastA:
	s_waitcnt vmcnt(0)
	v_cvt_pk_bf16_f32 v8, v8, v9
	v_cvt_pk_bf16_f32 v9, v10, v11
	v_cvt_pk_bf16_f32 v10, v12, v13
	v_cvt_pk_bf16_f32 v11, v14, v15
	global_store_dwordx4 v[4:5], v[8:11], off
	v_lshl_add_u64 v[4:5], v[4:5], 0, s[8:9]
	s_branch .Lxc_done
.Lxc_lastB:
	s_waitcnt vmcnt(0)
	v_cvt_pk_bf16_f32 v16, v16, v17
	v_cvt_pk_bf16_f32 v17, v18, v19
	v_cvt_pk_bf16_f32 v18, v20, v21
	v_cvt_pk_bf16_f32 v19, v22, v23
	global_store_dwordx4 v[4:5], v[16:19], off
	v_lshl_add_u64 v[4:5], v[4:5], 0, s[8:9]
.Lxc_done:
	s_or_b64 exec, exec, s[10:11]
	s_cmp_gt_i32 s57, 1
	s_cbranch_scc1 .LBB0_572
